# v05: + output-projection and MLP-down residual epilogues: gate vectors loaded once, 16 residual loads in flight with counted vmcnt (was 32 serialized load-vmcnt0-store round trips per tile)
# speedup vs baseline: 1.0189x; 1.0189x over previous
.LBB0_2367:
	ds_read_b128 v[142:145], v153
	ds_read_b128 v[146:149], v153 offset:1024
	ds_read_b128 v[156:159], v153 offset:2048
	ds_read_b128 v[160:163], v153 offset:3072
	s_add_i32 s69, s30, 2
	s_add_u32 s31, s28, 0xfff80080
	s_addc_u32 s34, s29, -1
	s_cmp_eq_u32 s66, s30
	s_cselect_b32 s30, s65, s67
	s_cselect_b32 s35, s5, s34
	s_cselect_b32 s34, s23, s31
	s_cselect_b32 s31, s21, s68
	v_lshl_add_u64 v[196:197], s[28:29], 0, v[134:135]
	s_add_i32 m0, s40, 0xc000
	ds_read_b128 v[164:167], v154
	ds_read_b128 v[168:171], v154 offset:1024
	ds_read_b128 v[172:175], v154 offset:2048
	ds_read_b128 v[176:179], v154 offset:3072
	ds_read_b128 v[180:183], v154 offset:4096
	ds_read_b128 v[184:187], v154 offset:5120
	ds_read_b128 v[188:191], v154 offset:6144
	ds_read_b128 v[192:195], v154 offset:7168
	global_load_lds_dwordx4 v[196:197], off
	v_lshl_add_u64 v[196:197], s[28:29], 0, v[136:137]
	s_add_i32 m0, s40, 0xe000
	s_nop 0
	global_load_lds_dwordx4 v[196:197], off
	s_waitcnt lgkmcnt(8)
	s_barrier
	s_waitcnt lgkmcnt(0)
	s_setprio 1
	s_waitcnt lgkmcnt(0)
	v_mfma_f32_16x16x32_bf16 v[124:127], v[142:145], v[164:167], v[124:127]
	v_mfma_f32_16x16x32_bf16 v[120:123], v[156:159], v[164:167], v[120:123]
	v_mfma_f32_16x16x32_bf16 v[116:119], v[142:145], v[172:175], v[116:119]
	v_mfma_f32_16x16x32_bf16 v[112:115], v[156:159], v[172:175], v[112:115]
	v_mfma_f32_16x16x32_bf16 v[100:103], v[142:145], v[180:183], v[100:103]
	v_mfma_f32_16x16x32_bf16 v[96:99], v[156:159], v[180:183], v[96:99]
	v_mfma_f32_16x16x32_bf16 v[84:87], v[142:145], v[188:191], v[84:87]
	v_mfma_f32_16x16x32_bf16 v[80:83], v[156:159], v[188:191], v[80:83]
	v_mfma_f32_16x16x32_bf16 v[124:127], v[146:149], v[168:171], v[124:127]
	v_mfma_f32_16x16x32_bf16 v[120:123], v[160:163], v[168:171], v[120:123]
	v_mfma_f32_16x16x32_bf16 v[116:119], v[146:149], v[176:179], v[116:119]
	v_mfma_f32_16x16x32_bf16 v[112:115], v[160:163], v[176:179], v[112:115]
	v_mfma_f32_16x16x32_bf16 v[100:103], v[146:149], v[184:187], v[100:103]
	v_mfma_f32_16x16x32_bf16 v[96:99], v[160:163], v[184:187], v[96:99]
	v_mfma_f32_16x16x32_bf16 v[84:87], v[146:149], v[192:195], v[84:87]
	v_mfma_f32_16x16x32_bf16 v[80:83], v[160:163], v[192:195], v[80:83]
	s_setprio 0
	s_barrier
	s_add_i32 s70, s54, s39
	v_lshl_add_u64 v[212:213], s[30:31], 0, v[128:129]
	s_mov_b32 m0, s70
	ds_read_b128 v[196:199], v155
	ds_read_b128 v[200:203], v155 offset:1024
	ds_read_b128 v[204:207], v155 offset:2048
	ds_read_b128 v[208:211], v155 offset:3072
	global_load_lds_dwordx4 v[212:213], off
	v_lshl_add_u64 v[214:215], s[30:31], 0, v[130:131]
	s_add_i32 m0, s70, 0x2000
	s_nop 0
	global_load_lds_dwordx4 v[214:215], off
	s_barrier
	s_waitcnt lgkmcnt(0)
	s_setprio 1
	s_waitcnt lgkmcnt(0)
	v_mfma_f32_16x16x32_bf16 v[108:111], v[196:199], v[164:167], v[108:111]
	v_mfma_f32_16x16x32_bf16 v[104:107], v[204:207], v[164:167], v[104:107]
	v_mfma_f32_16x16x32_bf16 v[92:95], v[196:199], v[172:175], v[92:95]
	v_mfma_f32_16x16x32_bf16 v[88:91], v[204:207], v[172:175], v[88:91]
	v_mfma_f32_16x16x32_bf16 v[76:79], v[196:199], v[180:183], v[76:79]
	v_mfma_f32_16x16x32_bf16 v[72:75], v[204:207], v[180:183], v[72:75]
	v_mfma_f32_16x16x32_bf16 v[68:71], v[196:199], v[188:191], v[68:71]
	v_mfma_f32_16x16x32_bf16 v[64:67], v[204:207], v[188:191], v[64:67]
	v_mfma_f32_16x16x32_bf16 v[108:111], v[200:203], v[168:171], v[108:111]
	v_mfma_f32_16x16x32_bf16 v[104:107], v[208:211], v[168:171], v[104:107]
	v_mfma_f32_16x16x32_bf16 v[92:95], v[200:203], v[176:179], v[92:95]
	v_mfma_f32_16x16x32_bf16 v[88:91], v[208:211], v[176:179], v[88:91]
	v_mfma_f32_16x16x32_bf16 v[76:79], v[200:203], v[184:187], v[76:79]
	v_mfma_f32_16x16x32_bf16 v[72:75], v[208:211], v[184:187], v[72:75]
	v_mfma_f32_16x16x32_bf16 v[68:71], v[200:203], v[192:195], v[68:71]
	v_mfma_f32_16x16x32_bf16 v[64:67], v[208:211], v[192:195], v[64:67]
	s_setprio 0
	s_mov_b32 m0, s40
	v_lshl_add_u64 v[218:219], s[34:35], 0, v[128:129]
	s_barrier
	ds_read_b128 v[164:167], v154 offset:16384
	ds_read_b128 v[168:171], v154 offset:17408
	ds_read_b128 v[172:175], v154 offset:18432
	ds_read_b128 v[176:179], v154 offset:19456
	ds_read_b128 v[180:183], v154 offset:20480
	ds_read_b128 v[184:187], v154 offset:21504
	ds_read_b128 v[188:191], v154 offset:22528
	ds_read_b128 v[192:195], v154 offset:23552
	global_load_lds_dwordx4 v[218:219], off
	v_lshl_add_u64 v[220:221], s[34:35], 0, v[130:131]
	s_mov_b32 m0, s41
	s_nop 0
	global_load_lds_dwordx4 v[220:221], off
	s_barrier
	s_waitcnt lgkmcnt(0)
	s_setprio 1
	s_waitcnt lgkmcnt(0)
	v_mfma_f32_16x16x32_bf16 v[60:63], v[142:145], v[164:167], v[60:63]
	v_mfma_f32_16x16x32_bf16 v[56:59], v[156:159], v[164:167], v[56:59]
	v_mfma_f32_16x16x32_bf16 v[52:55], v[142:145], v[172:175], v[52:55]
	v_mfma_f32_16x16x32_bf16 v[48:51], v[156:159], v[172:175], v[48:51]
	v_mfma_f32_16x16x32_bf16 v[40:43], v[142:145], v[180:183], v[40:43]
	v_mfma_f32_16x16x32_bf16 v[32:35], v[156:159], v[180:183], v[32:35]
	v_mfma_f32_16x16x32_bf16 v[24:27], v[142:145], v[188:191], v[24:27]
	v_mfma_f32_16x16x32_bf16 v[16:19], v[156:159], v[188:191], v[16:19]
	v_mfma_f32_16x16x32_bf16 v[60:63], v[146:149], v[168:171], v[60:63]
	v_mfma_f32_16x16x32_bf16 v[56:59], v[160:163], v[168:171], v[56:59]
	v_mfma_f32_16x16x32_bf16 v[52:55], v[146:149], v[176:179], v[52:55]
	v_mfma_f32_16x16x32_bf16 v[48:51], v[160:163], v[176:179], v[48:51]
	v_mfma_f32_16x16x32_bf16 v[40:43], v[146:149], v[184:187], v[40:43]
	v_mfma_f32_16x16x32_bf16 v[32:35], v[160:163], v[184:187], v[32:35]
	v_mfma_f32_16x16x32_bf16 v[24:27], v[146:149], v[192:195], v[24:27]
	v_mfma_f32_16x16x32_bf16 v[16:19], v[160:163], v[192:195], v[16:19]
	s_setprio 0
	s_barrier
	s_add_u32 s70, s30, 0x80000
	s_addc_u32 s71, s31, 0
	s_add_i32 s72, s56, s39
	v_lshl_add_u64 v[142:143], s[70:71], 0, v[128:129]
	s_mov_b32 m0, s72
	s_nop 0
	global_load_lds_dwordx4 v[142:143], off
	v_lshl_add_u64 v[142:143], s[70:71], 0, v[130:131]
	s_add_i32 m0, s72, 0x2000
	s_nop 0
	global_load_lds_dwordx4 v[142:143], off
	s_waitcnt vmcnt(6)
	s_barrier
	s_setprio 1
	v_mfma_f32_16x16x32_bf16 v[44:47], v[196:199], v[164:167], v[44:47]
	v_mfma_f32_16x16x32_bf16 v[36:39], v[204:207], v[164:167], v[36:39]
	v_mfma_f32_16x16x32_bf16 v[28:31], v[196:199], v[172:175], v[28:31]
	v_mfma_f32_16x16x32_bf16 v[20:23], v[204:207], v[172:175], v[20:23]
	v_mfma_f32_16x16x32_bf16 v[12:15], v[196:199], v[180:183], v[12:15]
	v_mfma_f32_16x16x32_bf16 v[8:11], v[204:207], v[180:183], v[8:11]
	v_mfma_f32_16x16x32_bf16 v[4:7], v[196:199], v[188:191], v[4:7]
	v_mfma_f32_16x16x32_bf16 v[0:3], v[204:207], v[188:191], v[0:3]
	v_mfma_f32_16x16x32_bf16 v[44:47], v[200:203], v[168:171], v[44:47]
	v_mfma_f32_16x16x32_bf16 v[36:39], v[208:211], v[168:171], v[36:39]
	v_mfma_f32_16x16x32_bf16 v[28:31], v[200:203], v[176:179], v[28:31]
	v_mfma_f32_16x16x32_bf16 v[20:23], v[208:211], v[176:179], v[20:23]
	v_mfma_f32_16x16x32_bf16 v[12:15], v[200:203], v[184:187], v[12:15]
	v_mfma_f32_16x16x32_bf16 v[8:11], v[208:211], v[184:187], v[8:11]
	v_mfma_f32_16x16x32_bf16 v[4:7], v[200:203], v[192:195], v[4:7]
	v_mfma_f32_16x16x32_bf16 v[0:3], v[208:211], v[192:195], v[0:3]
	s_setprio 0
	s_add_i32 s70, 0, 0x18000
	v_add_u32_e32 v132, s70, v152
	s_barrier
	ds_read_b128 v[142:145], v132
	ds_read_b128 v[146:149], v132 offset:1024
	ds_read_b128 v[156:159], v132 offset:2048
	ds_read_b128 v[160:163], v132 offset:3072
	s_add_u32 s34, s34, 0x80000
	s_addc_u32 s35, s35, 0
	s_mov_b32 m0, s42
	v_lshl_add_u64 v[196:197], s[34:35], 0, v[128:129]
	ds_read_b128 v[164:167], v154 offset:32768
	ds_read_b128 v[168:171], v154 offset:33792
	ds_read_b128 v[172:175], v154 offset:34816
	ds_read_b128 v[176:179], v154 offset:35840
	ds_read_b128 v[180:183], v154 offset:36864
	ds_read_b128 v[184:187], v154 offset:37888
	ds_read_b128 v[188:191], v154 offset:38912
	ds_read_b128 v[192:195], v154 offset:39936
	global_load_lds_dwordx4 v[196:197], off
	v_lshl_add_u64 v[196:197], s[34:35], 0, v[130:131]
	s_mov_b32 m0, s43
	s_nop 0
	global_load_lds_dwordx4 v[196:197], off
	s_waitcnt lgkmcnt(8)
	s_barrier
	s_waitcnt lgkmcnt(0)
	s_setprio 1
	s_waitcnt lgkmcnt(0)
	v_mfma_f32_16x16x32_bf16 v[124:127], v[142:145], v[164:167], v[124:127]
	v_mfma_f32_16x16x32_bf16 v[120:123], v[156:159], v[164:167], v[120:123]
	v_mfma_f32_16x16x32_bf16 v[116:119], v[142:145], v[172:175], v[116:119]
	v_mfma_f32_16x16x32_bf16 v[112:115], v[156:159], v[172:175], v[112:115]
	v_mfma_f32_16x16x32_bf16 v[100:103], v[142:145], v[180:183], v[100:103]
	v_mfma_f32_16x16x32_bf16 v[96:99], v[156:159], v[180:183], v[96:99]
	v_mfma_f32_16x16x32_bf16 v[84:87], v[142:145], v[188:191], v[84:87]
	v_mfma_f32_16x16x32_bf16 v[80:83], v[156:159], v[188:191], v[80:83]
	v_mfma_f32_16x16x32_bf16 v[124:127], v[146:149], v[168:171], v[124:127]
	v_mfma_f32_16x16x32_bf16 v[120:123], v[160:163], v[168:171], v[120:123]
	v_mfma_f32_16x16x32_bf16 v[116:119], v[146:149], v[176:179], v[116:119]
	v_mfma_f32_16x16x32_bf16 v[112:115], v[160:163], v[176:179], v[112:115]
	v_mfma_f32_16x16x32_bf16 v[100:103], v[146:149], v[184:187], v[100:103]
	v_mfma_f32_16x16x32_bf16 v[96:99], v[160:163], v[184:187], v[96:99]
	v_mfma_f32_16x16x32_bf16 v[84:87], v[146:149], v[192:195], v[84:87]
	v_mfma_f32_16x16x32_bf16 v[80:83], v[160:163], v[192:195], v[80:83]
	s_setprio 0
	s_barrier
	s_add_i32 s34, 0, 0x1c000
	s_add_i32 s35, s70, s39
	v_add_u32_e32 v132, s34, v152
	v_lshl_add_u64 v[212:213], v[212:213], 0, s[12:13]
	s_mov_b32 m0, s35
	ds_read_b128 v[196:199], v132
	ds_read_b128 v[200:203], v132 offset:1024
	ds_read_b128 v[204:207], v132 offset:2048
	ds_read_b128 v[208:211], v132 offset:3072
	global_load_lds_dwordx4 v[212:213], off
	v_lshl_add_u64 v[212:213], v[214:215], 0, s[12:13]
	s_add_i32 m0, s35, 0x2000
	s_nop 0
	global_load_lds_dwordx4 v[212:213], off
	s_barrier
	s_waitcnt lgkmcnt(0)
	s_setprio 1
	s_waitcnt lgkmcnt(0)
	v_mfma_f32_16x16x32_bf16 v[108:111], v[196:199], v[164:167], v[108:111]
	v_mfma_f32_16x16x32_bf16 v[104:107], v[204:207], v[164:167], v[104:107]
	v_mfma_f32_16x16x32_bf16 v[92:95], v[196:199], v[172:175], v[92:95]
	v_mfma_f32_16x16x32_bf16 v[88:91], v[204:207], v[172:175], v[88:91]
	v_mfma_f32_16x16x32_bf16 v[76:79], v[196:199], v[180:183], v[76:79]
	v_mfma_f32_16x16x32_bf16 v[72:75], v[204:207], v[180:183], v[72:75]
	v_mfma_f32_16x16x32_bf16 v[68:71], v[196:199], v[188:191], v[68:71]
	v_mfma_f32_16x16x32_bf16 v[64:67], v[204:207], v[188:191], v[64:67]
	v_mfma_f32_16x16x32_bf16 v[108:111], v[200:203], v[168:171], v[108:111]
	v_mfma_f32_16x16x32_bf16 v[104:107], v[208:211], v[168:171], v[104:107]
	v_mfma_f32_16x16x32_bf16 v[92:95], v[200:203], v[176:179], v[92:95]
	v_mfma_f32_16x16x32_bf16 v[88:91], v[208:211], v[176:179], v[88:91]
	v_mfma_f32_16x16x32_bf16 v[76:79], v[200:203], v[184:187], v[76:79]
	v_mfma_f32_16x16x32_bf16 v[72:75], v[208:211], v[184:187], v[72:75]
	v_mfma_f32_16x16x32_bf16 v[68:71], v[200:203], v[192:195], v[68:71]
	v_mfma_f32_16x16x32_bf16 v[64:67], v[208:211], v[192:195], v[64:67]
	s_setprio 0
	s_mov_b32 m0, s50
	v_lshl_add_u64 v[212:213], v[218:219], 0, s[12:13]
	s_barrier
	ds_read_b128 v[164:167], v154 offset:49152
	ds_read_b128 v[168:171], v154 offset:50176
	ds_read_b128 v[172:175], v154 offset:51200
	ds_read_b128 v[176:179], v154 offset:52224
	ds_read_b128 v[180:183], v154 offset:53248
	ds_read_b128 v[184:187], v154 offset:54272
	ds_read_b128 v[188:191], v154 offset:55296
	ds_read_b128 v[192:195], v154 offset:56320
	global_load_lds_dwordx4 v[212:213], off
	v_lshl_add_u64 v[212:213], v[220:221], 0, s[12:13]
	s_mov_b32 m0, s51
	s_nop 0
	global_load_lds_dwordx4 v[212:213], off
	s_barrier
	s_waitcnt lgkmcnt(0)
	s_setprio 1
	s_waitcnt lgkmcnt(0)
	v_mfma_f32_16x16x32_bf16 v[60:63], v[142:145], v[164:167], v[60:63]
	v_mfma_f32_16x16x32_bf16 v[56:59], v[156:159], v[164:167], v[56:59]
	v_mfma_f32_16x16x32_bf16 v[52:55], v[142:145], v[172:175], v[52:55]
	v_mfma_f32_16x16x32_bf16 v[48:51], v[156:159], v[172:175], v[48:51]
	v_mfma_f32_16x16x32_bf16 v[40:43], v[142:145], v[180:183], v[40:43]
	v_mfma_f32_16x16x32_bf16 v[32:35], v[156:159], v[180:183], v[32:35]
	v_mfma_f32_16x16x32_bf16 v[24:27], v[142:145], v[188:191], v[24:27]
	v_mfma_f32_16x16x32_bf16 v[16:19], v[156:159], v[188:191], v[16:19]
	v_mfma_f32_16x16x32_bf16 v[60:63], v[146:149], v[168:171], v[60:63]
	v_mfma_f32_16x16x32_bf16 v[56:59], v[160:163], v[168:171], v[56:59]
	v_mfma_f32_16x16x32_bf16 v[52:55], v[146:149], v[176:179], v[52:55]
	v_mfma_f32_16x16x32_bf16 v[48:51], v[160:163], v[176:179], v[48:51]
	v_mfma_f32_16x16x32_bf16 v[40:43], v[146:149], v[184:187], v[40:43]
	v_mfma_f32_16x16x32_bf16 v[32:35], v[160:163], v[184:187], v[32:35]
	v_mfma_f32_16x16x32_bf16 v[24:27], v[146:149], v[192:195], v[24:27]
	v_mfma_f32_16x16x32_bf16 v[16:19], v[160:163], v[192:195], v[16:19]
	s_setprio 0
	s_barrier
	s_add_u32 s30, s30, 0x80080
	s_addc_u32 s31, s31, 0
	s_add_i32 s34, s34, s39
	v_lshl_add_u64 v[142:143], s[30:31], 0, v[128:129]
	s_mov_b32 m0, s34
	s_nop 0
	global_load_lds_dwordx4 v[142:143], off
	v_lshl_add_u64 v[142:143], s[30:31], 0, v[130:131]
	s_add_i32 m0, s34, 0x2000
	s_nop 0
	global_load_lds_dwordx4 v[142:143], off
	s_waitcnt vmcnt(6)
	s_barrier
	s_setprio 1
	v_mfma_f32_16x16x32_bf16 v[44:47], v[196:199], v[164:167], v[44:47]
	v_mfma_f32_16x16x32_bf16 v[36:39], v[204:207], v[164:167], v[36:39]
	v_mfma_f32_16x16x32_bf16 v[28:31], v[196:199], v[172:175], v[28:31]
	v_mfma_f32_16x16x32_bf16 v[20:23], v[204:207], v[172:175], v[20:23]
	v_mfma_f32_16x16x32_bf16 v[12:15], v[196:199], v[180:183], v[12:15]
	v_mfma_f32_16x16x32_bf16 v[8:11], v[204:207], v[180:183], v[8:11]
	v_mfma_f32_16x16x32_bf16 v[4:7], v[196:199], v[188:191], v[4:7]
	v_mfma_f32_16x16x32_bf16 v[0:3], v[204:207], v[188:191], v[0:3]
	v_mfma_f32_16x16x32_bf16 v[44:47], v[200:203], v[168:171], v[44:47]
	v_mfma_f32_16x16x32_bf16 v[36:39], v[208:211], v[168:171], v[36:39]
	v_mfma_f32_16x16x32_bf16 v[28:31], v[200:203], v[176:179], v[28:31]
	v_mfma_f32_16x16x32_bf16 v[20:23], v[208:211], v[176:179], v[20:23]
	v_mfma_f32_16x16x32_bf16 v[12:15], v[200:203], v[184:187], v[12:15]
	v_mfma_f32_16x16x32_bf16 v[8:11], v[208:211], v[184:187], v[8:11]
	v_mfma_f32_16x16x32_bf16 v[4:7], v[200:203], v[192:195], v[4:7]
	v_mfma_f32_16x16x32_bf16 v[0:3], v[208:211], v[192:195], v[0:3]
	s_setprio 0
	s_add_u32 s28, s28, 0x100
	s_addc_u32 s29, s29, 0
	s_add_u32 s67, s67, 0x100
	s_addc_u32 s68, s68, 0
	s_cmp_ge_i32 s69, s64
	s_mov_b32 s30, s69
	s_barrier
	s_cbranch_scc0 .LBB0_2367
	v_mov_b32_e32 v132, v150
	v_mov_b32_e32 v142, v151
	s_lshl_b32 s5, s6, 8
	s_lshl_b32 s4, s4, 8
	s_add_i32 s5, s5, s48
	s_or_b32 s4, s4, s49
	v_add_u32_e32 v144, s5, v132
	v_lshl_add_u32 v142, v142, 2, s4
	s_mov_b64 s[4:5], -1
	s_cmp_eq_u32 s6, 32
	v_ashrrev_i32_e32 v156, 31, v144
	v_ashrrev_i32_e32 v143, 31, v142
	s_cbranch_scc1 .LBB0_2370
	v_readlane_b32 s64, v239, 3
	v_readlane_b32 s65, v239, 4
	v_lshlrev_b32_e32 v132, 13, v144
	v_ashrrev_i32_e32 v157, 12, v144
	v_lshl_add_u32 v132, v142, 2, v132
	v_mul_u32_u24_e32 v157, 0xc000, v157
	v_lshl_add_u32 v157, v142, 2, v157
	s_add_u32 s4, s8, 0x4000
	s_addc_u32 s5, s9, 0
	global_load_dwordx4 v[240:243], v157, s[4:5]
	global_load_dwordx4 v[244:247], v157, s[4:5] offset:64
	global_load_dwordx4 v[248:251], v157, s[4:5] offset:512
	global_load_dwordx4 v[252:255], v157, s[4:5] offset:576
	s_add_u32 s66, s64, 0x0
	s_addc_u32 s67, s65, 0
	global_load_dwordx4 v[156:159], v132, s[66:67]
	global_load_dwordx4 v[160:163], v132, s[66:67] offset:64
	global_load_dwordx4 v[164:167], v132, s[66:67] offset:512
	global_load_dwordx4 v[168:171], v132, s[66:67] offset:576
	s_add_u32 s66, s64, 0x20000
	s_addc_u32 s67, s65, 0
	global_load_dwordx4 v[172:175], v132, s[66:67]
	global_load_dwordx4 v[176:179], v132, s[66:67] offset:64
	global_load_dwordx4 v[180:183], v132, s[66:67] offset:512
	global_load_dwordx4 v[184:187], v132, s[66:67] offset:576
	s_add_u32 s66, s64, 0x40000
	s_addc_u32 s67, s65, 0
	global_load_dwordx4 v[188:191], v132, s[66:67]
	global_load_dwordx4 v[192:195], v132, s[66:67] offset:64
	global_load_dwordx4 v[196:199], v132, s[66:67] offset:512
	global_load_dwordx4 v[200:203], v132, s[66:67] offset:576
	s_add_u32 s66, s64, 0x60000
	s_addc_u32 s67, s65, 0
	global_load_dwordx4 v[204:207], v132, s[66:67]
	global_load_dwordx4 v[208:211], v132, s[66:67] offset:64
	global_load_dwordx4 v[142:145], v132, s[66:67] offset:512
	global_load_dwordx4 v[146:149], v132, s[66:67] offset:576
	s_add_u32 s68, s10, 0x0
	s_addc_u32 s69, s11, 0
	s_add_u32 s66, s64, 0x100000
	s_addc_u32 s67, s65, 0
	s_waitcnt vmcnt(15)
	v_pk_fma_f32 v[158:159], v[126:127], v[242:243], v[158:159]
	v_pk_fma_f32 v[156:157], v[124:125], v[240:241], v[156:157]
	global_store_dwordx4 v132, v[156:159], s[68:69]
	s_nop 1
	global_load_dwordx4 v[156:159], v132, s[66:67]
	s_waitcnt vmcnt(16)
	v_pk_fma_f32 v[162:163], v[122:123], v[246:247], v[162:163]
	v_pk_fma_f32 v[160:161], v[120:121], v[244:245], v[160:161]
	global_store_dwordx4 v132, v[160:163], s[68:69] offset:64
	s_nop 1
	global_load_dwordx4 v[160:163], v132, s[66:67] offset:64
	s_waitcnt vmcnt(17)
	v_pk_fma_f32 v[166:167], v[110:111], v[250:251], v[166:167]
	v_pk_fma_f32 v[164:165], v[108:109], v[248:249], v[164:165]
	global_store_dwordx4 v132, v[164:167], s[68:69] offset:512
	s_nop 1
	global_load_dwordx4 v[164:167], v132, s[66:67] offset:512
	s_waitcnt vmcnt(18)
	v_pk_fma_f32 v[170:171], v[106:107], v[254:255], v[170:171]
	v_pk_fma_f32 v[168:169], v[104:105], v[252:253], v[168:169]
	global_store_dwordx4 v132, v[168:171], s[68:69] offset:576
	s_nop 1
	global_load_dwordx4 v[168:171], v132, s[66:67] offset:576
	s_add_u32 s68, s10, 0x20000
	s_addc_u32 s69, s11, 0
	s_add_u32 s66, s64, 0x120000
	s_addc_u32 s67, s65, 0
	s_waitcnt vmcnt(19)
	v_pk_fma_f32 v[174:175], v[118:119], v[242:243], v[174:175]
	v_pk_fma_f32 v[172:173], v[116:117], v[240:241], v[172:173]
	global_store_dwordx4 v132, v[172:175], s[68:69]
	s_nop 1
	global_load_dwordx4 v[172:175], v132, s[66:67]
	s_waitcnt vmcnt(20)
	v_pk_fma_f32 v[178:179], v[114:115], v[246:247], v[178:179]
	v_pk_fma_f32 v[176:177], v[112:113], v[244:245], v[176:177]
	global_store_dwordx4 v132, v[176:179], s[68:69] offset:64
	s_nop 1
	global_load_dwordx4 v[176:179], v132, s[66:67] offset:64
	s_waitcnt vmcnt(21)
	v_pk_fma_f32 v[182:183], v[94:95], v[250:251], v[182:183]
	v_pk_fma_f32 v[180:181], v[92:93], v[248:249], v[180:181]
	global_store_dwordx4 v132, v[180:183], s[68:69] offset:512
	s_nop 1
	global_load_dwordx4 v[180:183], v132, s[66:67] offset:512
	s_waitcnt vmcnt(22)
	v_pk_fma_f32 v[186:187], v[90:91], v[254:255], v[186:187]
	v_pk_fma_f32 v[184:185], v[88:89], v[252:253], v[184:185]
	global_store_dwordx4 v132, v[184:187], s[68:69] offset:576
	s_nop 1
	global_load_dwordx4 v[184:187], v132, s[66:67] offset:576
	s_add_u32 s68, s10, 0x40000
	s_addc_u32 s69, s11, 0
	s_add_u32 s66, s64, 0x140000
	s_addc_u32 s67, s65, 0
	s_waitcnt vmcnt(23)
	v_pk_fma_f32 v[190:191], v[102:103], v[242:243], v[190:191]
	v_pk_fma_f32 v[188:189], v[100:101], v[240:241], v[188:189]
	global_store_dwordx4 v132, v[188:191], s[68:69]
	s_nop 1
	global_load_dwordx4 v[188:191], v132, s[66:67]
	s_waitcnt vmcnt(24)
	v_pk_fma_f32 v[194:195], v[98:99], v[246:247], v[194:195]
	v_pk_fma_f32 v[192:193], v[96:97], v[244:245], v[192:193]
	global_store_dwordx4 v132, v[192:195], s[68:69] offset:64
	s_nop 1
	global_load_dwordx4 v[192:195], v132, s[66:67] offset:64
	s_waitcnt vmcnt(25)
	v_pk_fma_f32 v[198:199], v[78:79], v[250:251], v[198:199]
	v_pk_fma_f32 v[196:197], v[76:77], v[248:249], v[196:197]
	global_store_dwordx4 v132, v[196:199], s[68:69] offset:512
	s_nop 1
	global_load_dwordx4 v[196:199], v132, s[66:67] offset:512
	s_waitcnt vmcnt(26)
	v_pk_fma_f32 v[202:203], v[74:75], v[254:255], v[202:203]
	v_pk_fma_f32 v[200:201], v[72:73], v[252:253], v[200:201]
	global_store_dwordx4 v132, v[200:203], s[68:69] offset:576
	s_nop 1
	global_load_dwordx4 v[200:203], v132, s[66:67] offset:576
	s_add_u32 s68, s10, 0x60000
	s_addc_u32 s69, s11, 0
	s_add_u32 s66, s64, 0x160000
	s_addc_u32 s67, s65, 0
	s_waitcnt vmcnt(27)
	v_pk_fma_f32 v[206:207], v[86:87], v[242:243], v[206:207]
	v_pk_fma_f32 v[204:205], v[84:85], v[240:241], v[204:205]
	global_store_dwordx4 v132, v[204:207], s[68:69]
	s_nop 1
	global_load_dwordx4 v[204:207], v132, s[66:67]
	s_waitcnt vmcnt(28)
	v_pk_fma_f32 v[210:211], v[82:83], v[246:247], v[210:211]
	v_pk_fma_f32 v[208:209], v[80:81], v[244:245], v[208:209]
	global_store_dwordx4 v132, v[208:211], s[68:69] offset:64
	s_nop 1
	global_load_dwordx4 v[208:211], v132, s[66:67] offset:64
	s_waitcnt vmcnt(29)
	v_pk_fma_f32 v[144:145], v[70:71], v[250:251], v[144:145]
	v_pk_fma_f32 v[142:143], v[68:69], v[248:249], v[142:143]
	global_store_dwordx4 v132, v[142:145], s[68:69] offset:512
	s_nop 1
	global_load_dwordx4 v[142:145], v132, s[66:67] offset:512
	s_waitcnt vmcnt(30)
	v_pk_fma_f32 v[148:149], v[66:67], v[254:255], v[148:149]
	v_pk_fma_f32 v[146:147], v[64:65], v[252:253], v[146:147]
	global_store_dwordx4 v132, v[146:149], s[68:69] offset:576
	s_nop 1
	global_load_dwordx4 v[146:149], v132, s[66:67] offset:576
	s_add_u32 s68, s10, 0x100000
	s_addc_u32 s69, s11, 0
	s_waitcnt vmcnt(30)
	v_pk_fma_f32 v[158:159], v[62:63], v[242:243], v[158:159]
	v_pk_fma_f32 v[156:157], v[60:61], v[240:241], v[156:157]
	global_store_dwordx4 v132, v[156:159], s[68:69]
	s_waitcnt vmcnt(29)
	v_pk_fma_f32 v[162:163], v[58:59], v[246:247], v[162:163]
	v_pk_fma_f32 v[160:161], v[56:57], v[244:245], v[160:161]
	global_store_dwordx4 v132, v[160:163], s[68:69] offset:64
	s_waitcnt vmcnt(28)
	v_pk_fma_f32 v[166:167], v[46:47], v[250:251], v[166:167]
	v_pk_fma_f32 v[164:165], v[44:45], v[248:249], v[164:165]
	global_store_dwordx4 v132, v[164:167], s[68:69] offset:512
	s_waitcnt vmcnt(27)
	v_pk_fma_f32 v[170:171], v[38:39], v[254:255], v[170:171]
	v_pk_fma_f32 v[168:169], v[36:37], v[252:253], v[168:169]
	global_store_dwordx4 v132, v[168:171], s[68:69] offset:576
	s_add_u32 s68, s10, 0x120000
	s_addc_u32 s69, s11, 0
	s_waitcnt vmcnt(26)
	v_pk_fma_f32 v[174:175], v[54:55], v[242:243], v[174:175]
	v_pk_fma_f32 v[172:173], v[52:53], v[240:241], v[172:173]
	global_store_dwordx4 v132, v[172:175], s[68:69]
	s_waitcnt vmcnt(25)
	v_pk_fma_f32 v[178:179], v[50:51], v[246:247], v[178:179]
	v_pk_fma_f32 v[176:177], v[48:49], v[244:245], v[176:177]
	global_store_dwordx4 v132, v[176:179], s[68:69] offset:64
	s_waitcnt vmcnt(24)
	v_pk_fma_f32 v[182:183], v[30:31], v[250:251], v[182:183]
	v_pk_fma_f32 v[180:181], v[28:29], v[248:249], v[180:181]
	global_store_dwordx4 v132, v[180:183], s[68:69] offset:512
	s_waitcnt vmcnt(23)
	v_pk_fma_f32 v[186:187], v[22:23], v[254:255], v[186:187]
	v_pk_fma_f32 v[184:185], v[20:21], v[252:253], v[184:185]
	global_store_dwordx4 v132, v[184:187], s[68:69] offset:576
	s_add_u32 s68, s10, 0x140000
	s_addc_u32 s69, s11, 0
	s_waitcnt vmcnt(22)
	v_pk_fma_f32 v[190:191], v[42:43], v[242:243], v[190:191]
	v_pk_fma_f32 v[188:189], v[40:41], v[240:241], v[188:189]
	global_store_dwordx4 v132, v[188:191], s[68:69]
	s_waitcnt vmcnt(21)
	v_pk_fma_f32 v[194:195], v[34:35], v[246:247], v[194:195]
	v_pk_fma_f32 v[192:193], v[32:33], v[244:245], v[192:193]
	global_store_dwordx4 v132, v[192:195], s[68:69] offset:64
	s_waitcnt vmcnt(20)
	v_pk_fma_f32 v[198:199], v[14:15], v[250:251], v[198:199]
	v_pk_fma_f32 v[196:197], v[12:13], v[248:249], v[196:197]
	global_store_dwordx4 v132, v[196:199], s[68:69] offset:512
	s_waitcnt vmcnt(19)
	v_pk_fma_f32 v[202:203], v[10:11], v[254:255], v[202:203]
	v_pk_fma_f32 v[200:201], v[8:9], v[252:253], v[200:201]
	global_store_dwordx4 v132, v[200:203], s[68:69] offset:576
	s_add_u32 s68, s10, 0x160000
	s_addc_u32 s69, s11, 0
	s_waitcnt vmcnt(18)
	v_pk_fma_f32 v[206:207], v[26:27], v[242:243], v[206:207]
	v_pk_fma_f32 v[204:205], v[24:25], v[240:241], v[204:205]
	global_store_dwordx4 v132, v[204:207], s[68:69]
	s_waitcnt vmcnt(17)
	v_pk_fma_f32 v[210:211], v[18:19], v[246:247], v[210:211]
	v_pk_fma_f32 v[208:209], v[16:17], v[244:245], v[208:209]
	global_store_dwordx4 v132, v[208:211], s[68:69] offset:64
	s_waitcnt vmcnt(16)
	v_pk_fma_f32 v[144:145], v[6:7], v[250:251], v[144:145]
	v_pk_fma_f32 v[142:143], v[4:5], v[248:249], v[142:143]
	global_store_dwordx4 v132, v[142:145], s[68:69] offset:512
	s_waitcnt vmcnt(15)
	v_pk_fma_f32 v[148:149], v[2:3], v[254:255], v[148:149]
	v_pk_fma_f32 v[146:147], v[0:1], v[252:253], v[146:147]
	global_store_dwordx4 v132, v[146:149], s[68:69] offset:576
	v_readlane_b32 s66, v239, 5
	v_readlane_b32 s67, v239, 6
	v_readlane_b32 s68, v239, 7
	v_readlane_b32 s69, v239, 8
	v_readlane_b32 s70, v239, 9
	v_readlane_b32 s71, v239, 10
	v_readlane_b32 s72, v239, 11
	v_readlane_b32 s73, v239, 12
	v_readlane_b32 s74, v239, 13
	v_readlane_b32 s75, v239, 14
	v_readlane_b32 s76, v239, 15
	v_readlane_b32 s77, v239, 16
	v_readlane_b32 s78, v239, 17
	v_readlane_b32 s79, v239, 18
	s_mov_b64 s[4:5], 0

.LBB0_2783:
	ds_read_b128 v[140:143], v153
	ds_read_b128 v[144:147], v153 offset:1024
	ds_read_b128 v[156:159], v153 offset:2048
	ds_read_b128 v[160:163], v153 offset:3072
	s_add_i32 s72, s28, 2
	s_add_u32 s29, s26, 0xffe00080
	s_addc_u32 s30, s27, -1
	s_cmp_eq_u32 s69, s28
	s_cselect_b32 s28, s68, s70
	s_cselect_b32 s31, s19, s30
	s_cselect_b32 s30, s25, s29
	s_cselect_b32 s29, s17, s71
	v_lshl_add_u64 v[148:149], s[26:27], 0, v[132:133]
	s_add_i32 m0, s38, 0xc000
	ds_read_b128 v[164:167], v154
	ds_read_b128 v[168:171], v154 offset:1024
	ds_read_b128 v[172:175], v154 offset:2048
	ds_read_b128 v[176:179], v154 offset:3072
	ds_read_b128 v[180:183], v154 offset:4096
	ds_read_b128 v[184:187], v154 offset:5120
	ds_read_b128 v[188:191], v154 offset:6144
	ds_read_b128 v[192:195], v154 offset:7168
	global_load_lds_dwordx4 v[148:149], off
	v_lshl_add_u64 v[148:149], s[26:27], 0, v[134:135]
	s_add_i32 m0, s38, 0xe000
	s_nop 0
	global_load_lds_dwordx4 v[148:149], off
	s_waitcnt lgkmcnt(8)
	s_barrier
	s_waitcnt lgkmcnt(0)
	s_setprio 1
	s_waitcnt lgkmcnt(0)
	v_mfma_f32_16x16x32_bf16 v[124:127], v[140:143], v[164:167], v[124:127]
	v_mfma_f32_16x16x32_bf16 v[120:123], v[156:159], v[164:167], v[120:123]
	v_mfma_f32_16x16x32_bf16 v[116:119], v[140:143], v[172:175], v[116:119]
	v_mfma_f32_16x16x32_bf16 v[112:115], v[156:159], v[172:175], v[112:115]
	v_mfma_f32_16x16x32_bf16 v[104:107], v[140:143], v[180:183], v[104:107]
	v_mfma_f32_16x16x32_bf16 v[96:99], v[156:159], v[180:183], v[96:99]
	v_mfma_f32_16x16x32_bf16 v[88:91], v[140:143], v[188:191], v[88:91]
	v_mfma_f32_16x16x32_bf16 v[80:83], v[156:159], v[188:191], v[80:83]
	v_mfma_f32_16x16x32_bf16 v[124:127], v[144:147], v[168:171], v[124:127]
	v_mfma_f32_16x16x32_bf16 v[120:123], v[160:163], v[168:171], v[120:123]
	v_mfma_f32_16x16x32_bf16 v[116:119], v[144:147], v[176:179], v[116:119]
	v_mfma_f32_16x16x32_bf16 v[112:115], v[160:163], v[176:179], v[112:115]
	v_mfma_f32_16x16x32_bf16 v[104:107], v[144:147], v[184:187], v[104:107]
	v_mfma_f32_16x16x32_bf16 v[96:99], v[160:163], v[184:187], v[96:99]
	v_mfma_f32_16x16x32_bf16 v[88:91], v[144:147], v[192:195], v[88:91]
	v_mfma_f32_16x16x32_bf16 v[80:83], v[160:163], v[192:195], v[80:83]
	s_setprio 0
	s_barrier
	s_add_i32 s73, s52, s37
	v_lshl_add_u64 v[148:149], s[28:29], 0, v[128:129]
	s_mov_b32 m0, s73
	ds_read_b128 v[196:199], v155
	ds_read_b128 v[200:203], v155 offset:1024
	ds_read_b128 v[204:207], v155 offset:2048
	ds_read_b128 v[208:211], v155 offset:3072
	global_load_lds_dwordx4 v[148:149], off
	v_lshl_add_u64 v[212:213], s[28:29], 0, v[130:131]
	s_add_i32 m0, s73, 0x2000
	s_nop 0
	global_load_lds_dwordx4 v[212:213], off
	s_barrier
	s_waitcnt lgkmcnt(0)
	s_setprio 1
	s_waitcnt lgkmcnt(0)
	v_mfma_f32_16x16x32_bf16 v[108:111], v[196:199], v[164:167], v[108:111]
	v_mfma_f32_16x16x32_bf16 v[100:103], v[204:207], v[164:167], v[100:103]
	v_mfma_f32_16x16x32_bf16 v[92:95], v[196:199], v[172:175], v[92:95]
	v_mfma_f32_16x16x32_bf16 v[84:87], v[204:207], v[172:175], v[84:87]
	v_mfma_f32_16x16x32_bf16 v[76:79], v[196:199], v[180:183], v[76:79]
	v_mfma_f32_16x16x32_bf16 v[72:75], v[204:207], v[180:183], v[72:75]
	v_mfma_f32_16x16x32_bf16 v[68:71], v[196:199], v[188:191], v[68:71]
	v_mfma_f32_16x16x32_bf16 v[64:67], v[204:207], v[188:191], v[64:67]
	v_mfma_f32_16x16x32_bf16 v[108:111], v[200:203], v[168:171], v[108:111]
	v_mfma_f32_16x16x32_bf16 v[100:103], v[208:211], v[168:171], v[100:103]
	v_mfma_f32_16x16x32_bf16 v[92:95], v[200:203], v[176:179], v[92:95]
	v_mfma_f32_16x16x32_bf16 v[84:87], v[208:211], v[176:179], v[84:87]
	v_mfma_f32_16x16x32_bf16 v[76:79], v[200:203], v[184:187], v[76:79]
	v_mfma_f32_16x16x32_bf16 v[72:75], v[208:211], v[184:187], v[72:75]
	v_mfma_f32_16x16x32_bf16 v[68:71], v[200:203], v[192:195], v[68:71]
	v_mfma_f32_16x16x32_bf16 v[64:67], v[208:211], v[192:195], v[64:67]
	s_setprio 0
	s_mov_b32 m0, s38
	v_lshl_add_u64 v[214:215], s[30:31], 0, v[128:129]
	s_barrier
	ds_read_b128 v[164:167], v154 offset:16384
	ds_read_b128 v[168:171], v154 offset:17408
	ds_read_b128 v[172:175], v154 offset:18432
	ds_read_b128 v[176:179], v154 offset:19456
	ds_read_b128 v[180:183], v154 offset:20480
	ds_read_b128 v[184:187], v154 offset:21504
	ds_read_b128 v[188:191], v154 offset:22528
	ds_read_b128 v[192:195], v154 offset:23552
	global_load_lds_dwordx4 v[214:215], off
	v_lshl_add_u64 v[218:219], s[30:31], 0, v[130:131]
	s_mov_b32 m0, s39
	s_nop 0
	global_load_lds_dwordx4 v[218:219], off
	s_barrier
	s_waitcnt lgkmcnt(0)
	s_setprio 1
	s_waitcnt lgkmcnt(0)
	v_mfma_f32_16x16x32_bf16 v[60:63], v[140:143], v[164:167], v[60:63]
	v_mfma_f32_16x16x32_bf16 v[56:59], v[156:159], v[164:167], v[56:59]
	v_mfma_f32_16x16x32_bf16 v[52:55], v[140:143], v[172:175], v[52:55]
	v_mfma_f32_16x16x32_bf16 v[48:51], v[156:159], v[172:175], v[48:51]
	v_mfma_f32_16x16x32_bf16 v[44:47], v[140:143], v[180:183], v[44:47]
	v_mfma_f32_16x16x32_bf16 v[36:39], v[156:159], v[180:183], v[36:39]
	v_mfma_f32_16x16x32_bf16 v[28:31], v[140:143], v[188:191], v[28:31]
	v_mfma_f32_16x16x32_bf16 v[20:23], v[156:159], v[188:191], v[20:23]
	v_mfma_f32_16x16x32_bf16 v[60:63], v[144:147], v[168:171], v[60:63]
	v_mfma_f32_16x16x32_bf16 v[56:59], v[160:163], v[168:171], v[56:59]
	v_mfma_f32_16x16x32_bf16 v[52:55], v[144:147], v[176:179], v[52:55]
	v_mfma_f32_16x16x32_bf16 v[48:51], v[160:163], v[176:179], v[48:51]
	v_mfma_f32_16x16x32_bf16 v[44:47], v[144:147], v[184:187], v[44:47]
	v_mfma_f32_16x16x32_bf16 v[36:39], v[160:163], v[184:187], v[36:39]
	v_mfma_f32_16x16x32_bf16 v[28:31], v[144:147], v[192:195], v[28:31]
	v_mfma_f32_16x16x32_bf16 v[20:23], v[160:163], v[192:195], v[20:23]
	s_setprio 0
	s_barrier
	s_add_u32 s74, s28, 0x200000
	s_addc_u32 s75, s29, 0
	s_add_i32 s73, s54, s37
	v_lshl_add_u64 v[140:141], s[74:75], 0, v[128:129]
	s_mov_b32 m0, s73
	s_nop 0
	global_load_lds_dwordx4 v[140:141], off
	v_lshl_add_u64 v[140:141], s[74:75], 0, v[130:131]
	s_add_i32 m0, s73, 0x2000
	s_nop 0
	global_load_lds_dwordx4 v[140:141], off
	s_waitcnt vmcnt(6)
	s_barrier
	s_setprio 1
	v_mfma_f32_16x16x32_bf16 v[40:43], v[196:199], v[164:167], v[40:43]
	v_mfma_f32_16x16x32_bf16 v[32:35], v[204:207], v[164:167], v[32:35]
	v_mfma_f32_16x16x32_bf16 v[24:27], v[196:199], v[172:175], v[24:27]
	v_mfma_f32_16x16x32_bf16 v[16:19], v[204:207], v[172:175], v[16:19]
	v_mfma_f32_16x16x32_bf16 v[12:15], v[196:199], v[180:183], v[12:15]
	v_mfma_f32_16x16x32_bf16 v[8:11], v[204:207], v[180:183], v[8:11]
	v_mfma_f32_16x16x32_bf16 v[4:7], v[196:199], v[188:191], v[4:7]
	v_mfma_f32_16x16x32_bf16 v[0:3], v[204:207], v[188:191], v[0:3]
	v_mfma_f32_16x16x32_bf16 v[40:43], v[200:203], v[168:171], v[40:43]
	v_mfma_f32_16x16x32_bf16 v[32:35], v[208:211], v[168:171], v[32:35]
	v_mfma_f32_16x16x32_bf16 v[24:27], v[200:203], v[176:179], v[24:27]
	v_mfma_f32_16x16x32_bf16 v[16:19], v[208:211], v[176:179], v[16:19]
	v_mfma_f32_16x16x32_bf16 v[12:15], v[200:203], v[184:187], v[12:15]
	v_mfma_f32_16x16x32_bf16 v[8:11], v[208:211], v[184:187], v[8:11]
	v_mfma_f32_16x16x32_bf16 v[4:7], v[200:203], v[192:195], v[4:7]
	v_mfma_f32_16x16x32_bf16 v[0:3], v[208:211], v[192:195], v[0:3]
	s_setprio 0
	s_add_i32 s73, 0, 0x18000
	v_add_u32_e32 v160, s73, v152
	s_barrier
	ds_read_b128 v[140:143], v160
	ds_read_b128 v[144:147], v160 offset:1024
	ds_read_b128 v[156:159], v160 offset:2048
	ds_read_b128 v[160:163], v160 offset:3072
	s_add_u32 s30, s30, 0x200000
	s_addc_u32 s31, s31, 0
	s_mov_b32 m0, s40
	v_lshl_add_u64 v[196:197], s[30:31], 0, v[128:129]
	ds_read_b128 v[164:167], v154 offset:32768
	ds_read_b128 v[168:171], v154 offset:33792
	ds_read_b128 v[172:175], v154 offset:34816
	ds_read_b128 v[176:179], v154 offset:35840
	ds_read_b128 v[180:183], v154 offset:36864
	ds_read_b128 v[184:187], v154 offset:37888
	ds_read_b128 v[188:191], v154 offset:38912
	ds_read_b128 v[192:195], v154 offset:39936
	global_load_lds_dwordx4 v[196:197], off
	v_lshl_add_u64 v[196:197], s[30:31], 0, v[130:131]
	s_mov_b32 m0, s41
	s_nop 0
	global_load_lds_dwordx4 v[196:197], off
	s_waitcnt lgkmcnt(8)
	s_barrier
	s_waitcnt lgkmcnt(0)
	s_setprio 1
	s_waitcnt lgkmcnt(0)
	v_mfma_f32_16x16x32_bf16 v[124:127], v[140:143], v[164:167], v[124:127]
	v_mfma_f32_16x16x32_bf16 v[120:123], v[156:159], v[164:167], v[120:123]
	v_mfma_f32_16x16x32_bf16 v[116:119], v[140:143], v[172:175], v[116:119]
	v_mfma_f32_16x16x32_bf16 v[112:115], v[156:159], v[172:175], v[112:115]
	v_mfma_f32_16x16x32_bf16 v[104:107], v[140:143], v[180:183], v[104:107]
	v_mfma_f32_16x16x32_bf16 v[96:99], v[156:159], v[180:183], v[96:99]
	v_mfma_f32_16x16x32_bf16 v[88:91], v[140:143], v[188:191], v[88:91]
	v_mfma_f32_16x16x32_bf16 v[80:83], v[156:159], v[188:191], v[80:83]
	v_mfma_f32_16x16x32_bf16 v[124:127], v[144:147], v[168:171], v[124:127]
	v_mfma_f32_16x16x32_bf16 v[120:123], v[160:163], v[168:171], v[120:123]
	v_mfma_f32_16x16x32_bf16 v[116:119], v[144:147], v[176:179], v[116:119]
	v_mfma_f32_16x16x32_bf16 v[112:115], v[160:163], v[176:179], v[112:115]
	v_mfma_f32_16x16x32_bf16 v[104:107], v[144:147], v[184:187], v[104:107]
	v_mfma_f32_16x16x32_bf16 v[96:99], v[160:163], v[184:187], v[96:99]
	v_mfma_f32_16x16x32_bf16 v[88:91], v[144:147], v[192:195], v[88:91]
	v_mfma_f32_16x16x32_bf16 v[80:83], v[160:163], v[192:195], v[80:83]
	s_setprio 0
	s_barrier
	s_add_i32 s30, 0, 0x1c000
	s_add_i32 s31, s73, s37
	v_add_u32_e32 v208, s30, v152
	v_lshl_add_u64 v[148:149], v[148:149], 0, s[10:11]
	s_mov_b32 m0, s31
	ds_read_b128 v[196:199], v208
	ds_read_b128 v[200:203], v208 offset:1024
	ds_read_b128 v[204:207], v208 offset:2048
	ds_read_b128 v[208:211], v208 offset:3072
	global_load_lds_dwordx4 v[148:149], off
	v_lshl_add_u64 v[148:149], v[212:213], 0, s[10:11]
	s_add_i32 m0, s31, 0x2000
	s_nop 0
	global_load_lds_dwordx4 v[148:149], off
	s_barrier
	s_waitcnt lgkmcnt(0)
	s_setprio 1
	s_waitcnt lgkmcnt(0)
	v_mfma_f32_16x16x32_bf16 v[108:111], v[196:199], v[164:167], v[108:111]
	v_mfma_f32_16x16x32_bf16 v[100:103], v[204:207], v[164:167], v[100:103]
	v_mfma_f32_16x16x32_bf16 v[92:95], v[196:199], v[172:175], v[92:95]
	v_mfma_f32_16x16x32_bf16 v[84:87], v[204:207], v[172:175], v[84:87]
	v_mfma_f32_16x16x32_bf16 v[76:79], v[196:199], v[180:183], v[76:79]
	v_mfma_f32_16x16x32_bf16 v[72:75], v[204:207], v[180:183], v[72:75]
	v_mfma_f32_16x16x32_bf16 v[68:71], v[196:199], v[188:191], v[68:71]
	v_mfma_f32_16x16x32_bf16 v[64:67], v[204:207], v[188:191], v[64:67]
	v_mfma_f32_16x16x32_bf16 v[108:111], v[200:203], v[168:171], v[108:111]
	v_mfma_f32_16x16x32_bf16 v[100:103], v[208:211], v[168:171], v[100:103]
	v_mfma_f32_16x16x32_bf16 v[92:95], v[200:203], v[176:179], v[92:95]
	v_mfma_f32_16x16x32_bf16 v[84:87], v[208:211], v[176:179], v[84:87]
	v_mfma_f32_16x16x32_bf16 v[76:79], v[200:203], v[184:187], v[76:79]
	v_mfma_f32_16x16x32_bf16 v[72:75], v[208:211], v[184:187], v[72:75]
	v_mfma_f32_16x16x32_bf16 v[68:71], v[200:203], v[192:195], v[68:71]
	v_mfma_f32_16x16x32_bf16 v[64:67], v[208:211], v[192:195], v[64:67]
	s_setprio 0
	s_mov_b32 m0, s47
	v_lshl_add_u64 v[148:149], v[214:215], 0, s[10:11]
	s_barrier
	ds_read_b128 v[164:167], v154 offset:49152
	ds_read_b128 v[168:171], v154 offset:50176
	ds_read_b128 v[172:175], v154 offset:51200
	ds_read_b128 v[176:179], v154 offset:52224
	ds_read_b128 v[180:183], v154 offset:53248
	ds_read_b128 v[184:187], v154 offset:54272
	ds_read_b128 v[188:191], v154 offset:55296
	ds_read_b128 v[192:195], v154 offset:56320
	global_load_lds_dwordx4 v[148:149], off
	v_lshl_add_u64 v[148:149], v[218:219], 0, s[10:11]
	s_mov_b32 m0, s48
	s_nop 0
	global_load_lds_dwordx4 v[148:149], off
	s_barrier
	s_waitcnt lgkmcnt(0)
	s_setprio 1
	s_waitcnt lgkmcnt(0)
	v_mfma_f32_16x16x32_bf16 v[60:63], v[140:143], v[164:167], v[60:63]
	v_mfma_f32_16x16x32_bf16 v[56:59], v[156:159], v[164:167], v[56:59]
	v_mfma_f32_16x16x32_bf16 v[52:55], v[140:143], v[172:175], v[52:55]
	v_mfma_f32_16x16x32_bf16 v[48:51], v[156:159], v[172:175], v[48:51]
	v_mfma_f32_16x16x32_bf16 v[44:47], v[140:143], v[180:183], v[44:47]
	v_mfma_f32_16x16x32_bf16 v[36:39], v[156:159], v[180:183], v[36:39]
	v_mfma_f32_16x16x32_bf16 v[28:31], v[140:143], v[188:191], v[28:31]
	v_mfma_f32_16x16x32_bf16 v[20:23], v[156:159], v[188:191], v[20:23]
	v_mfma_f32_16x16x32_bf16 v[60:63], v[144:147], v[168:171], v[60:63]
	v_mfma_f32_16x16x32_bf16 v[56:59], v[160:163], v[168:171], v[56:59]
	v_mfma_f32_16x16x32_bf16 v[52:55], v[144:147], v[176:179], v[52:55]
	v_mfma_f32_16x16x32_bf16 v[48:51], v[160:163], v[176:179], v[48:51]
	v_mfma_f32_16x16x32_bf16 v[44:47], v[144:147], v[184:187], v[44:47]
	v_mfma_f32_16x16x32_bf16 v[36:39], v[160:163], v[184:187], v[36:39]
	v_mfma_f32_16x16x32_bf16 v[28:31], v[144:147], v[192:195], v[28:31]
	v_mfma_f32_16x16x32_bf16 v[20:23], v[160:163], v[192:195], v[20:23]
	s_setprio 0
	s_barrier
	s_add_u32 s28, s28, 0x200080
	s_addc_u32 s29, s29, 0
	s_add_i32 s30, s30, s37
	v_lshl_add_u64 v[140:141], s[28:29], 0, v[128:129]
	s_mov_b32 m0, s30
	s_nop 0
	global_load_lds_dwordx4 v[140:141], off
	v_lshl_add_u64 v[140:141], s[28:29], 0, v[130:131]
	s_add_i32 m0, s30, 0x2000
	s_nop 0
	global_load_lds_dwordx4 v[140:141], off
	s_waitcnt vmcnt(6)
	s_barrier
	s_setprio 1
	v_mfma_f32_16x16x32_bf16 v[40:43], v[196:199], v[164:167], v[40:43]
	v_mfma_f32_16x16x32_bf16 v[32:35], v[204:207], v[164:167], v[32:35]
	v_mfma_f32_16x16x32_bf16 v[24:27], v[196:199], v[172:175], v[24:27]
	v_mfma_f32_16x16x32_bf16 v[16:19], v[204:207], v[172:175], v[16:19]
	v_mfma_f32_16x16x32_bf16 v[12:15], v[196:199], v[180:183], v[12:15]
	v_mfma_f32_16x16x32_bf16 v[8:11], v[204:207], v[180:183], v[8:11]
	v_mfma_f32_16x16x32_bf16 v[4:7], v[196:199], v[188:191], v[4:7]
	v_mfma_f32_16x16x32_bf16 v[0:3], v[204:207], v[188:191], v[0:3]
	v_mfma_f32_16x16x32_bf16 v[40:43], v[200:203], v[168:171], v[40:43]
	v_mfma_f32_16x16x32_bf16 v[32:35], v[208:211], v[168:171], v[32:35]
	v_mfma_f32_16x16x32_bf16 v[24:27], v[200:203], v[176:179], v[24:27]
	v_mfma_f32_16x16x32_bf16 v[16:19], v[208:211], v[176:179], v[16:19]
	v_mfma_f32_16x16x32_bf16 v[12:15], v[200:203], v[184:187], v[12:15]
	v_mfma_f32_16x16x32_bf16 v[8:11], v[208:211], v[184:187], v[8:11]
	v_mfma_f32_16x16x32_bf16 v[4:7], v[200:203], v[192:195], v[4:7]
	v_mfma_f32_16x16x32_bf16 v[0:3], v[208:211], v[192:195], v[0:3]
	s_setprio 0
	s_add_u32 s26, s26, 0x100
	s_addc_u32 s27, s27, 0
	s_add_u32 s70, s70, 0x100
	s_addc_u32 s71, s71, 0
	s_cmp_ge_i32 s72, s67
	s_mov_b32 s28, s72
	s_barrier
	s_cbranch_scc0 .LBB0_2783
	s_lshl_b32 s17, s4, 8
	v_mov_b32_e32 v140, v150
	v_mov_b32_e32 v141, v151
	s_add_i32 s17, s17, s45
	s_nop 0
	v_add_u32_e32 v146, s17, v140
	s_lshl_b32 s17, s24, 8
	s_or_b32 s17, s17, s46
	v_lshl_add_u32 v140, v141, 2, s17
	s_cmp_eq_u32 s4, 32
	v_ashrrev_i32_e32 v141, 31, v140
	v_add_u32_e32 v142, 0xffffe000, v146
	s_mov_b64 s[24:25], -1
	s_cbranch_scc1 .LBB0_2786
	v_lshlrev_b32_e32 v148, 13, v146
	v_ashrrev_i32_e32 v149, 12, v146
	v_lshl_add_u32 v148, v140, 2, v148
	v_mul_u32_u24_e32 v149, 0xc000, v149
	v_lshl_add_u32 v149, v140, 2, v149
	s_add_u32 s80, s8, 0xa000
	s_addc_u32 s81, s9, 0
	global_load_dwordx4 v[240:243], v149, s[80:81]
	global_load_dwordx4 v[244:247], v149, s[80:81] offset:64
	global_load_dwordx4 v[248:251], v149, s[80:81] offset:512
	global_load_dwordx4 v[252:255], v149, s[80:81] offset:576
	s_add_u32 s76, s6, 0x0
	s_addc_u32 s77, s7, 0
	global_load_dwordx4 v[156:159], v148, s[76:77]
	global_load_dwordx4 v[160:163], v148, s[76:77] offset:64
	global_load_dwordx4 v[164:167], v148, s[76:77] offset:512
	global_load_dwordx4 v[168:171], v148, s[76:77] offset:576
	s_add_u32 s76, s6, 0x20000
	s_addc_u32 s77, s7, 0
	global_load_dwordx4 v[172:175], v148, s[76:77]
	global_load_dwordx4 v[176:179], v148, s[76:77] offset:64
	global_load_dwordx4 v[180:183], v148, s[76:77] offset:512
	global_load_dwordx4 v[184:187], v148, s[76:77] offset:576
	s_add_u32 s76, s6, 0x40000
	s_addc_u32 s77, s7, 0
	global_load_dwordx4 v[188:191], v148, s[76:77]
	global_load_dwordx4 v[192:195], v148, s[76:77] offset:64
	global_load_dwordx4 v[196:199], v148, s[76:77] offset:512
	global_load_dwordx4 v[200:203], v148, s[76:77] offset:576
	s_add_u32 s76, s6, 0x60000
	s_addc_u32 s77, s7, 0
	global_load_dwordx4 v[204:207], v148, s[76:77]
	global_load_dwordx4 v[208:211], v148, s[76:77] offset:64
	global_load_dwordx4 v[140:143], v148, s[76:77] offset:512
	global_load_dwordx4 v[144:147], v148, s[76:77] offset:576
	s_add_u32 s78, s88, 0x0
	s_addc_u32 s79, s89, 0
	s_add_u32 s76, s6, 0x100000
	s_addc_u32 s77, s7, 0
	s_waitcnt vmcnt(15)
	v_pk_fma_f32 v[158:159], v[126:127], v[242:243], v[158:159]
	v_pk_fma_f32 v[156:157], v[124:125], v[240:241], v[156:157]
	global_store_dwordx4 v148, v[156:159], s[78:79]
	s_nop 1
	global_load_dwordx4 v[156:159], v148, s[76:77]
	s_waitcnt vmcnt(16)
	v_pk_fma_f32 v[162:163], v[122:123], v[246:247], v[162:163]
	v_pk_fma_f32 v[160:161], v[120:121], v[244:245], v[160:161]
	global_store_dwordx4 v148, v[160:163], s[78:79] offset:64
	s_nop 1
	global_load_dwordx4 v[160:163], v148, s[76:77] offset:64
	s_waitcnt vmcnt(17)
	v_pk_fma_f32 v[166:167], v[110:111], v[250:251], v[166:167]
	v_pk_fma_f32 v[164:165], v[108:109], v[248:249], v[164:165]
	global_store_dwordx4 v148, v[164:167], s[78:79] offset:512
	s_nop 1
	global_load_dwordx4 v[164:167], v148, s[76:77] offset:512
	s_waitcnt vmcnt(18)
	v_pk_fma_f32 v[170:171], v[102:103], v[254:255], v[170:171]
	v_pk_fma_f32 v[168:169], v[100:101], v[252:253], v[168:169]
	global_store_dwordx4 v148, v[168:171], s[78:79] offset:576
	s_nop 1
	global_load_dwordx4 v[168:171], v148, s[76:77] offset:576
	s_add_u32 s78, s88, 0x20000
	s_addc_u32 s79, s89, 0
	s_add_u32 s76, s6, 0x120000
	s_addc_u32 s77, s7, 0
	s_waitcnt vmcnt(19)
	v_pk_fma_f32 v[174:175], v[118:119], v[242:243], v[174:175]
	v_pk_fma_f32 v[172:173], v[116:117], v[240:241], v[172:173]
	global_store_dwordx4 v148, v[172:175], s[78:79]
	s_nop 1
	global_load_dwordx4 v[172:175], v148, s[76:77]
	s_waitcnt vmcnt(20)
	v_pk_fma_f32 v[178:179], v[114:115], v[246:247], v[178:179]
	v_pk_fma_f32 v[176:177], v[112:113], v[244:245], v[176:177]
	global_store_dwordx4 v148, v[176:179], s[78:79] offset:64
	s_nop 1
	global_load_dwordx4 v[176:179], v148, s[76:77] offset:64
	s_waitcnt vmcnt(21)
	v_pk_fma_f32 v[182:183], v[94:95], v[250:251], v[182:183]
	v_pk_fma_f32 v[180:181], v[92:93], v[248:249], v[180:181]
	global_store_dwordx4 v148, v[180:183], s[78:79] offset:512
	s_nop 1
	global_load_dwordx4 v[180:183], v148, s[76:77] offset:512
	s_waitcnt vmcnt(22)
	v_pk_fma_f32 v[186:187], v[86:87], v[254:255], v[186:187]
	v_pk_fma_f32 v[184:185], v[84:85], v[252:253], v[184:185]
	global_store_dwordx4 v148, v[184:187], s[78:79] offset:576
	s_nop 1
	global_load_dwordx4 v[184:187], v148, s[76:77] offset:576
	s_add_u32 s78, s88, 0x40000
	s_addc_u32 s79, s89, 0
	s_add_u32 s76, s6, 0x140000
	s_addc_u32 s77, s7, 0
	s_waitcnt vmcnt(23)
	v_pk_fma_f32 v[190:191], v[106:107], v[242:243], v[190:191]
	v_pk_fma_f32 v[188:189], v[104:105], v[240:241], v[188:189]
	global_store_dwordx4 v148, v[188:191], s[78:79]
	s_nop 1
	global_load_dwordx4 v[188:191], v148, s[76:77]
	s_waitcnt vmcnt(24)
	v_pk_fma_f32 v[194:195], v[98:99], v[246:247], v[194:195]
	v_pk_fma_f32 v[192:193], v[96:97], v[244:245], v[192:193]
	global_store_dwordx4 v148, v[192:195], s[78:79] offset:64
	s_nop 1
	global_load_dwordx4 v[192:195], v148, s[76:77] offset:64
	s_waitcnt vmcnt(25)
	v_pk_fma_f32 v[198:199], v[78:79], v[250:251], v[198:199]
	v_pk_fma_f32 v[196:197], v[76:77], v[248:249], v[196:197]
	global_store_dwordx4 v148, v[196:199], s[78:79] offset:512
	s_nop 1
	global_load_dwordx4 v[196:199], v148, s[76:77] offset:512
	s_waitcnt vmcnt(26)
	v_pk_fma_f32 v[202:203], v[74:75], v[254:255], v[202:203]
	v_pk_fma_f32 v[200:201], v[72:73], v[252:253], v[200:201]
	global_store_dwordx4 v148, v[200:203], s[78:79] offset:576
	s_nop 1
	global_load_dwordx4 v[200:203], v148, s[76:77] offset:576
	s_add_u32 s78, s88, 0x60000
	s_addc_u32 s79, s89, 0
	s_add_u32 s76, s6, 0x160000
	s_addc_u32 s77, s7, 0
	s_waitcnt vmcnt(27)
	v_pk_fma_f32 v[206:207], v[90:91], v[242:243], v[206:207]
	v_pk_fma_f32 v[204:205], v[88:89], v[240:241], v[204:205]
	global_store_dwordx4 v148, v[204:207], s[78:79]
	s_nop 1
	global_load_dwordx4 v[204:207], v148, s[76:77]
	s_waitcnt vmcnt(28)
	v_pk_fma_f32 v[210:211], v[82:83], v[246:247], v[210:211]
	v_pk_fma_f32 v[208:209], v[80:81], v[244:245], v[208:209]
	global_store_dwordx4 v148, v[208:211], s[78:79] offset:64
	s_nop 1
	global_load_dwordx4 v[208:211], v148, s[76:77] offset:64
	s_waitcnt vmcnt(29)
	v_pk_fma_f32 v[142:143], v[70:71], v[250:251], v[142:143]
	v_pk_fma_f32 v[140:141], v[68:69], v[248:249], v[140:141]
	global_store_dwordx4 v148, v[140:143], s[78:79] offset:512
	s_nop 1
	global_load_dwordx4 v[140:143], v148, s[76:77] offset:512
	s_waitcnt vmcnt(30)
	v_pk_fma_f32 v[146:147], v[66:67], v[254:255], v[146:147]
	v_pk_fma_f32 v[144:145], v[64:65], v[252:253], v[144:145]
	global_store_dwordx4 v148, v[144:147], s[78:79] offset:576
	s_nop 1
	global_load_dwordx4 v[144:147], v148, s[76:77] offset:576
	s_add_u32 s78, s88, 0x100000
	s_addc_u32 s79, s89, 0
	s_waitcnt vmcnt(30)
	v_pk_fma_f32 v[158:159], v[62:63], v[242:243], v[158:159]
	v_pk_fma_f32 v[156:157], v[60:61], v[240:241], v[156:157]
	global_store_dwordx4 v148, v[156:159], s[78:79]
	s_waitcnt vmcnt(29)
	v_pk_fma_f32 v[162:163], v[58:59], v[246:247], v[162:163]
	v_pk_fma_f32 v[160:161], v[56:57], v[244:245], v[160:161]
	global_store_dwordx4 v148, v[160:163], s[78:79] offset:64
	s_waitcnt vmcnt(28)
	v_pk_fma_f32 v[166:167], v[42:43], v[250:251], v[166:167]
	v_pk_fma_f32 v[164:165], v[40:41], v[248:249], v[164:165]
	global_store_dwordx4 v148, v[164:167], s[78:79] offset:512
	s_waitcnt vmcnt(27)
	v_pk_fma_f32 v[170:171], v[34:35], v[254:255], v[170:171]
	v_pk_fma_f32 v[168:169], v[32:33], v[252:253], v[168:169]
	global_store_dwordx4 v148, v[168:171], s[78:79] offset:576
	s_add_u32 s78, s88, 0x120000
	s_addc_u32 s79, s89, 0
	s_waitcnt vmcnt(26)
	v_pk_fma_f32 v[174:175], v[54:55], v[242:243], v[174:175]
	v_pk_fma_f32 v[172:173], v[52:53], v[240:241], v[172:173]
	global_store_dwordx4 v148, v[172:175], s[78:79]
	s_waitcnt vmcnt(25)
	v_pk_fma_f32 v[178:179], v[50:51], v[246:247], v[178:179]
	v_pk_fma_f32 v[176:177], v[48:49], v[244:245], v[176:177]
	global_store_dwordx4 v148, v[176:179], s[78:79] offset:64
	s_waitcnt vmcnt(24)
	v_pk_fma_f32 v[182:183], v[26:27], v[250:251], v[182:183]
	v_pk_fma_f32 v[180:181], v[24:25], v[248:249], v[180:181]
	global_store_dwordx4 v148, v[180:183], s[78:79] offset:512
	s_waitcnt vmcnt(23)
	v_pk_fma_f32 v[186:187], v[18:19], v[254:255], v[186:187]
	v_pk_fma_f32 v[184:185], v[16:17], v[252:253], v[184:185]
	global_store_dwordx4 v148, v[184:187], s[78:79] offset:576
	s_add_u32 s78, s88, 0x140000
	s_addc_u32 s79, s89, 0
	s_waitcnt vmcnt(22)
	v_pk_fma_f32 v[190:191], v[46:47], v[242:243], v[190:191]
	v_pk_fma_f32 v[188:189], v[44:45], v[240:241], v[188:189]
	global_store_dwordx4 v148, v[188:191], s[78:79]
	s_waitcnt vmcnt(21)
	v_pk_fma_f32 v[194:195], v[38:39], v[246:247], v[194:195]
	v_pk_fma_f32 v[192:193], v[36:37], v[244:245], v[192:193]
	global_store_dwordx4 v148, v[192:195], s[78:79] offset:64
	s_waitcnt vmcnt(20)
	v_pk_fma_f32 v[198:199], v[14:15], v[250:251], v[198:199]
	v_pk_fma_f32 v[196:197], v[12:13], v[248:249], v[196:197]
	global_store_dwordx4 v148, v[196:199], s[78:79] offset:512
	s_waitcnt vmcnt(19)
	v_pk_fma_f32 v[202:203], v[10:11], v[254:255], v[202:203]
	v_pk_fma_f32 v[200:201], v[8:9], v[252:253], v[200:201]
	global_store_dwordx4 v148, v[200:203], s[78:79] offset:576
	s_add_u32 s78, s88, 0x160000
	s_addc_u32 s79, s89, 0
	s_waitcnt vmcnt(18)
	v_pk_fma_f32 v[206:207], v[30:31], v[242:243], v[206:207]
	v_pk_fma_f32 v[204:205], v[28:29], v[240:241], v[204:205]
	global_store_dwordx4 v148, v[204:207], s[78:79]
	s_waitcnt vmcnt(17)
	v_pk_fma_f32 v[210:211], v[22:23], v[246:247], v[210:211]
	v_pk_fma_f32 v[208:209], v[20:21], v[244:245], v[208:209]
	global_store_dwordx4 v148, v[208:211], s[78:79] offset:64
	s_waitcnt vmcnt(16)
	v_pk_fma_f32 v[142:143], v[6:7], v[250:251], v[142:143]
	v_pk_fma_f32 v[140:141], v[4:5], v[248:249], v[140:141]
	global_store_dwordx4 v148, v[140:143], s[78:79] offset:512
	s_waitcnt vmcnt(15)
	v_pk_fma_f32 v[146:147], v[2:3], v[254:255], v[146:147]
	v_pk_fma_f32 v[144:145], v[0:1], v[252:253], v[144:145]
	global_store_dwordx4 v148, v[144:147], s[78:79] offset:576
	s_mov_b64 s[24:25], 0
